# RG-LRU finalize carry scan: 4 chunks per trip with 16 loads in flight (was one dependent round trip per chunk)
# baseline (speedup 1.0000x reference)
; __device__ void lru_final_item(const Params& P, int l, int item) {
;     ...
;   for (int jj = 0; jj < j; ++jj) {
;     const float* ap = P.AP + (size_t)(b * 64 + jj) * 512 + lane * 8;
;     const float* he = P.HE + (size_t)(b * 64 + jj) * 512 + lane * 8;
;     const float4 a0 = *(const float4*)ap, a1 = *(const float4*)(ap + 4);
;     const float4 h0 = *(const float4*)he, h1 = *(const float4*)(he + 4);
;     carry[0] = a0.x * carry[0] + h0.x; carry[1] = a0.y * carry[1] + h0.y; carry[2] = a0.z * carry[2] + h0.z; carry[3] = a0.w * carry[3] + h0.w;
;     carry[4] = a1.x * carry[4] + h1.x; carry[5] = a1.y * carry[5] + h1.y; carry[6] = a1.z * carry[6] + h1.z; carry[7] = a1.w * carry[7] + h1.w;
;   }
.Llf_chunk:
	s_sub_u32 s38, s4, s0
	s_cmp_lt_u32 s38, 0x2000
	s_cbranch_scc1 .Llf_tail
	v_lshl_add_u64 v[56:57], v[2:3], 0, s[0:1]
	v_lshl_add_u64 v[58:59], v[0:1], 0, s[0:1]
	global_load_dwordx4 v[60:63], v[58:59], off offset:16
	global_load_dwordx4 v[64:67], v[56:57], off offset:16
	global_load_dwordx4 v[68:71], v[56:57], off
	global_load_dwordx4 v[72:75], v[58:59], off
	s_add_u32 s0, s0, 0x800
	s_addc_u32 s1, s1, 0
	v_lshl_add_u64 v[56:57], v[2:3], 0, s[0:1]
	v_lshl_add_u64 v[58:59], v[0:1], 0, s[0:1]
	global_load_dwordx4 v[76:79], v[58:59], off offset:16
	global_load_dwordx4 v[80:83], v[56:57], off offset:16
	global_load_dwordx4 v[84:87], v[56:57], off
	global_load_dwordx4 v[88:91], v[58:59], off
	s_add_u32 s0, s0, 0x800
	s_addc_u32 s1, s1, 0
	v_lshl_add_u64 v[56:57], v[2:3], 0, s[0:1]
	v_lshl_add_u64 v[58:59], v[0:1], 0, s[0:1]
	global_load_dwordx4 v[92:95], v[58:59], off offset:16
	global_load_dwordx4 v[96:99], v[56:57], off offset:16
	global_load_dwordx4 v[100:103], v[56:57], off
	global_load_dwordx4 v[104:107], v[58:59], off
	s_add_u32 s0, s0, 0x800
	s_addc_u32 s1, s1, 0
	v_lshl_add_u64 v[56:57], v[2:3], 0, s[0:1]
	v_lshl_add_u64 v[58:59], v[0:1], 0, s[0:1]
	global_load_dwordx4 v[108:111], v[58:59], off offset:16
	global_load_dwordx4 v[112:115], v[56:57], off offset:16
	global_load_dwordx4 v[116:119], v[56:57], off
	global_load_dwordx4 v[120:123], v[58:59], off
	s_add_u32 s0, s0, 0x800
	s_addc_u32 s1, s1, 0
	s_waitcnt vmcnt(14)
	v_pk_fma_f32 v[14:15], v[14:15], v[66:67], v[62:63]
	v_pk_fma_f32 v[12:13], v[12:13], v[64:65], v[60:61]
	s_waitcnt vmcnt(12)
	v_pk_fma_f32 v[10:11], v[10:11], v[70:71], v[74:75]
	v_pk_fma_f32 v[8:9], v[8:9], v[68:69], v[72:73]
	s_waitcnt vmcnt(10)
	v_pk_fma_f32 v[14:15], v[14:15], v[82:83], v[78:79]
	v_pk_fma_f32 v[12:13], v[12:13], v[80:81], v[76:77]
	s_waitcnt vmcnt(8)
	v_pk_fma_f32 v[10:11], v[10:11], v[86:87], v[90:91]
	v_pk_fma_f32 v[8:9], v[8:9], v[84:85], v[88:89]
	s_waitcnt vmcnt(6)
	v_pk_fma_f32 v[14:15], v[14:15], v[98:99], v[94:95]
	v_pk_fma_f32 v[12:13], v[12:13], v[96:97], v[92:93]
	s_waitcnt vmcnt(4)
	v_pk_fma_f32 v[10:11], v[10:11], v[102:103], v[106:107]
	v_pk_fma_f32 v[8:9], v[8:9], v[100:101], v[104:105]
	s_waitcnt vmcnt(2)
	v_pk_fma_f32 v[14:15], v[14:15], v[114:115], v[110:111]
	v_pk_fma_f32 v[12:13], v[12:13], v[112:113], v[108:109]
	s_waitcnt vmcnt(0)
	v_pk_fma_f32 v[10:11], v[10:11], v[118:119], v[122:123]
	v_pk_fma_f32 v[8:9], v[8:9], v[116:117], v[120:121]
	s_branch .Llf_chunk
.Llf_tail:
	s_cmp_eq_u32 s4, s0
	s_cbranch_scc1 .LBB0_217
